# v78: spatial-GEMM epilogue: the 4 per-row bias values fetched once up front instead of 16 single loads each followed by a full drain
# speedup vs baseline: 1.0032x; 1.0032x over previous
.LBB0_397:
	v_mov_b32_e32 v179, v235
	v_mov_b32_e32 v239, v236
	s_lshl_b32 s81, s17, 8
	v_add_u32_e32 v0, s67, v179
	v_add_u32_e32 v186, s81, v0
	s_cmp_lt_i32 s47, 5
	s_mov_b64 s[2:3], -1
	s_cbranch_scc1 .LBB0_407
	s_cmp_lt_i32 s47, 6
	s_cbranch_scc1 .LBB0_404
	s_cmp_gt_i32 s47, 6
	s_cbranch_scc0 .LBB0_401
	s_lshl_b32 s2, s48, 8
	s_or_b32 s2, s2, s68
	v_lshl_add_u32 v218, v239, 3, s2
	v_lshl_add_u32 v138, s12, 8, v0
	v_readlane_b32 s14, v255, 20
	v_readlane_b32 s15, v255, 21
	s_lshl_b32 s3, s48, 7
	v_add_u32_e32 v174, 0, v138
	v_and_b32_e32 v174, 0x7f, v174
	v_or_b32_e32 v174, s3, v174
	v_lshlrev_b32_e32 v174, 2, v174
	global_load_dword v170, v174, s[14:15]
	v_add_u32_e32 v174, 16, v138
	v_and_b32_e32 v174, 0x7f, v174
	v_or_b32_e32 v174, s3, v174
	v_lshlrev_b32_e32 v174, 2, v174
	global_load_dword v171, v174, s[14:15]
	v_add_u32_e32 v174, 32, v138
	v_and_b32_e32 v174, 0x7f, v174
	v_or_b32_e32 v174, s3, v174
	v_lshlrev_b32_e32 v174, 2, v174
	global_load_dword v172, v174, s[14:15]
	v_add_u32_e32 v174, 48, v138
	v_and_b32_e32 v174, 0x7f, v174
	v_or_b32_e32 v174, s3, v174
	v_lshlrev_b32_e32 v174, 2, v174
	global_load_dword v173, v174, s[14:15]
	v_ashrrev_i32_e32 v219, 31, v218
	v_lshlrev_b64 v[196:197], 1, v[218:219]
	v_ashrrev_i32_e32 v139, 31, v138
	v_add_u32_e32 v206, 16, v138
	v_lshl_add_u64 v[140:141], s[76:77], 0, v[196:197]
	v_lshlrev_b64 v[204:205], 11, v[138:139]
	v_ashrrev_i32_e32 v207, 31, v206
	v_add_u32_e32 v208, 32, v138
	v_lshl_add_u64 v[220:221], v[218:219], 2, s[36:37]
	v_lshl_add_u64 v[142:143], v[140:141], 0, v[204:205]
	v_lshlrev_b64 v[202:203], 11, v[206:207]
	v_ashrrev_i32_e32 v209, 31, v208
	v_add_u32_e32 v210, 48, v138
	global_load_dwordx4 v[130:133], v[220:221], off offset:16
	global_load_dwordx4 v[134:137], v[220:221], off
	global_load_dwordx4 v[240:243], v[142:143], off
	v_lshl_add_u64 v[142:143], v[140:141], 0, v[202:203]
	v_lshlrev_b64 v[200:201], 11, v[208:209]
	v_ashrrev_i32_e32 v211, 31, v210
	global_load_dwordx4 v[162:165], v[142:143], off
	v_lshl_add_u64 v[142:143], v[140:141], 0, v[200:201]
	v_lshlrev_b64 v[198:199], 11, v[210:211]
	s_mov_b64 s[2:3], 0x40000
	v_add_u32_e32 v212, 0x90, v138
	global_load_dwordx4 v[158:161], v[142:143], off
	v_lshl_add_u64 v[142:143], v[140:141], 0, v[198:199]
	v_lshl_add_u64 v[194:195], v[204:205], 0, s[2:3]
	v_ashrrev_i32_e32 v213, 31, v212
	v_add_u32_e32 v214, 0xa0, v138
	v_add_u32_e32 v216, 0xb0, v138
	v_readlane_b32 s8, v255, 9
	global_load_dwordx4 v[154:157], v[142:143], off
	v_lshl_add_u64 v[142:143], v[140:141], 0, v[194:195]
	v_lshlrev_b64 v[192:193], 11, v[212:213]
	v_ashrrev_i32_e32 v215, 31, v214
	v_ashrrev_i32_e32 v217, 31, v216
	v_readlane_b32 s9, v255, 10
	s_lshl_b32 s2, s48, 7
	v_and_b32_e32 v0, 0x7f, v0
	global_load_dwordx4 v[150:153], v[142:143], off
	v_lshl_add_u64 v[142:143], v[140:141], 0, v[192:193]
	v_lshlrev_b64 v[190:191], 11, v[214:215]
	v_lshlrev_b64 v[188:189], 11, v[216:217]
	v_lshl_add_u64 v[222:223], s[8:9], 0, v[196:197]
	v_or_b32_e32 v196, s2, v0
	v_readlane_b32 s10, v255, 20
	global_load_dwordx4 v[146:149], v[142:143], off
	v_lshl_add_u64 v[142:143], v[140:141], 0, v[190:191]
	v_lshl_add_u64 v[138:139], v[140:141], 0, v[188:189]
	v_ashrrev_i32_e32 v197, 31, v196
	v_readlane_b32 s11, v255, 21
	global_load_dwordx4 v[142:145], v[142:143], off
	s_waitcnt vmcnt(0)
	v_lshlrev_b32_e32 v252, 16, v240
	global_load_dwordx4 v[138:141], v[138:139], off
	v_lshl_add_u64 v[196:197], v[196:197], 2, s[10:11]
	global_load_dword v0, v[196:197], off
	v_and_b32_e32 v253, 0xffff0000, v240
	s_waitcnt vmcnt(0)
	v_pk_fma_f32 v[246:247], v[126:127], v[134:135], v[0:1] op_sel_hi:[1,1,0]
	s_nop 0
	v_pk_mul_f32 v[246:247], v[246:247], v[252:253]
	v_pk_fma_f32 v[244:245], v[128:129], v[136:137], v[0:1] op_sel_hi:[1,1,0]
	v_cvt_pk_bf16_f32 v240, v246, v247
	v_lshlrev_b32_e32 v246, 16, v241
	v_and_b32_e32 v247, 0xffff0000, v241
	v_pk_mul_f32 v[244:245], v[244:245], v[246:247]
	v_pk_fma_f32 v[250:251], v[122:123], v[130:131], v[0:1] op_sel_hi:[1,1,0]
	v_cvt_pk_bf16_f32 v241, v244, v245
	v_lshlrev_b32_e32 v244, 16, v242
	v_and_b32_e32 v245, 0xffff0000, v242
	v_pk_mul_f32 v[244:245], v[250:251], v[244:245]
	v_pk_fma_f32 v[248:249], v[124:125], v[132:133], v[0:1] op_sel_hi:[1,1,0]
	v_cvt_pk_bf16_f32 v242, v244, v245
	v_lshlrev_b32_e32 v244, 16, v243
	v_and_b32_e32 v245, 0xffff0000, v243
	v_and_b32_e32 v0, 0x7f, v206
	v_pk_mul_f32 v[244:245], v[248:249], v[244:245]
	v_or_b32_e32 v206, s2, v0
	v_cvt_pk_bf16_f32 v243, v244, v245
	v_lshl_add_u64 v[244:245], v[222:223], 0, v[204:205]
	v_ashrrev_i32_e32 v207, 31, v206
	global_store_dwordx4 v[244:245], v[240:243], off
	v_lshl_add_u64 v[206:207], v[206:207], 2, s[10:11]
	v_mov_b32_e32 v0, v171
	v_lshlrev_b32_e32 v248, 16, v162
	v_and_b32_e32 v249, 0xffff0000, v162
	v_pk_fma_f32 v[242:243], v[110:111], v[134:135], v[0:1] op_sel_hi:[1,1,0]
	s_nop 0
	v_pk_mul_f32 v[242:243], v[242:243], v[248:249]
	v_pk_fma_f32 v[240:241], v[112:113], v[136:137], v[0:1] op_sel_hi:[1,1,0]
	v_cvt_pk_bf16_f32 v162, v242, v243
	v_lshlrev_b32_e32 v242, 16, v163
	v_and_b32_e32 v243, 0xffff0000, v163
	v_pk_mul_f32 v[240:241], v[240:241], v[242:243]
	v_pk_fma_f32 v[246:247], v[106:107], v[130:131], v[0:1] op_sel_hi:[1,1,0]
	v_cvt_pk_bf16_f32 v163, v240, v241
	v_lshlrev_b32_e32 v240, 16, v164
	v_and_b32_e32 v241, 0xffff0000, v164
	v_pk_mul_f32 v[240:241], v[246:247], v[240:241]
	v_pk_fma_f32 v[244:245], v[108:109], v[132:133], v[0:1] op_sel_hi:[1,1,0]
	v_cvt_pk_bf16_f32 v164, v240, v241
	v_lshlrev_b32_e32 v240, 16, v165
	v_and_b32_e32 v241, 0xffff0000, v165
	v_pk_mul_f32 v[240:241], v[244:245], v[240:241]
	v_and_b32_e32 v0, 0x7f, v208
	v_cvt_pk_bf16_f32 v165, v240, v241
	v_lshl_add_u64 v[240:241], v[222:223], 0, v[202:203]
	global_store_dwordx4 v[240:241], v[162:165], off
	v_lshlrev_b32_e32 v244, 16, v158
	v_and_b32_e32 v245, 0xffff0000, v158
	v_or_b32_e32 v162, s2, v0
	v_ashrrev_i32_e32 v163, 31, v162
	v_lshl_add_u64 v[208:209], v[162:163], 2, s[10:11]
	v_mov_b32_e32 v0, v172
	v_pk_fma_f32 v[164:165], v[94:95], v[134:135], v[0:1] op_sel_hi:[1,1,0]
	s_nop 0
	v_pk_mul_f32 v[164:165], v[164:165], v[244:245]
	v_pk_fma_f32 v[162:163], v[96:97], v[136:137], v[0:1] op_sel_hi:[1,1,0]
	v_cvt_pk_bf16_f32 v158, v164, v165
	v_lshlrev_b32_e32 v164, 16, v159
	v_and_b32_e32 v165, 0xffff0000, v159
	v_pk_mul_f32 v[162:163], v[162:163], v[164:165]
	v_pk_fma_f32 v[242:243], v[90:91], v[130:131], v[0:1] op_sel_hi:[1,1,0]
	v_cvt_pk_bf16_f32 v159, v162, v163
	v_lshlrev_b32_e32 v162, 16, v160
	v_and_b32_e32 v163, 0xffff0000, v160
	v_pk_mul_f32 v[162:163], v[242:243], v[162:163]
	v_pk_fma_f32 v[240:241], v[92:93], v[132:133], v[0:1] op_sel_hi:[1,1,0]
	v_cvt_pk_bf16_f32 v160, v162, v163
	v_lshlrev_b32_e32 v162, 16, v161
	v_and_b32_e32 v163, 0xffff0000, v161
	v_pk_mul_f32 v[162:163], v[240:241], v[162:163]
	v_and_b32_e32 v0, 0x7f, v210
	v_cvt_pk_bf16_f32 v161, v162, v163
	v_lshl_add_u64 v[162:163], v[222:223], 0, v[200:201]
	global_store_dwordx4 v[162:163], v[158:161], off
	v_lshlrev_b32_e32 v240, 16, v154
	v_and_b32_e32 v241, 0xffff0000, v154
	v_or_b32_e32 v158, s2, v0
	v_ashrrev_i32_e32 v159, 31, v158
	v_lshl_add_u64 v[210:211], v[158:159], 2, s[10:11]
	v_mov_b32_e32 v0, v173
	v_pk_fma_f32 v[160:161], v[78:79], v[134:135], v[0:1] op_sel_hi:[1,1,0]
	s_nop 0
	v_pk_mul_f32 v[160:161], v[160:161], v[240:241]
	v_pk_fma_f32 v[158:159], v[80:81], v[136:137], v[0:1] op_sel_hi:[1,1,0]
	v_cvt_pk_bf16_f32 v154, v160, v161
	v_lshlrev_b32_e32 v160, 16, v155
	v_and_b32_e32 v161, 0xffff0000, v155
	v_pk_mul_f32 v[158:159], v[158:159], v[160:161]
	v_pk_fma_f32 v[164:165], v[74:75], v[130:131], v[0:1] op_sel_hi:[1,1,0]
	v_cvt_pk_bf16_f32 v155, v158, v159
	v_lshlrev_b32_e32 v158, 16, v156
	v_and_b32_e32 v159, 0xffff0000, v156
	v_pk_mul_f32 v[158:159], v[164:165], v[158:159]
	v_pk_fma_f32 v[162:163], v[76:77], v[132:133], v[0:1] op_sel_hi:[1,1,0]
	v_cvt_pk_bf16_f32 v156, v158, v159
	v_lshlrev_b32_e32 v158, 16, v157
	v_and_b32_e32 v159, 0xffff0000, v157
	v_pk_mul_f32 v[158:159], v[162:163], v[158:159]
	v_lshlrev_b32_e32 v162, 16, v150
	v_cvt_pk_bf16_f32 v157, v158, v159
	v_lshl_add_u64 v[158:159], v[222:223], 0, v[198:199]
	global_store_dwordx4 v[158:159], v[154:157], off
	v_mov_b32_e32 v0, v170
	v_and_b32_e32 v163, 0xffff0000, v150
	v_pk_fma_f32 v[156:157], v[62:63], v[134:135], v[0:1] op_sel_hi:[1,1,0]
	s_nop 0
	v_pk_mul_f32 v[156:157], v[156:157], v[162:163]
	v_pk_fma_f32 v[154:155], v[64:65], v[136:137], v[0:1] op_sel_hi:[1,1,0]
	v_cvt_pk_bf16_f32 v150, v156, v157
	v_lshlrev_b32_e32 v156, 16, v151
	v_and_b32_e32 v157, 0xffff0000, v151
	v_pk_mul_f32 v[154:155], v[154:155], v[156:157]
	v_pk_fma_f32 v[160:161], v[58:59], v[130:131], v[0:1] op_sel_hi:[1,1,0]
	v_cvt_pk_bf16_f32 v151, v154, v155
	v_lshlrev_b32_e32 v154, 16, v152
	v_and_b32_e32 v155, 0xffff0000, v152
	v_pk_mul_f32 v[154:155], v[160:161], v[154:155]
	v_pk_fma_f32 v[158:159], v[60:61], v[132:133], v[0:1] op_sel_hi:[1,1,0]
	v_cvt_pk_bf16_f32 v152, v154, v155
	v_lshlrev_b32_e32 v154, 16, v153
	v_and_b32_e32 v155, 0xffff0000, v153
	v_pk_mul_f32 v[154:155], v[158:159], v[154:155]
	v_and_b32_e32 v0, 0x7f, v212
	v_cvt_pk_bf16_f32 v153, v154, v155
	v_lshl_add_u64 v[154:155], v[222:223], 0, v[194:195]
	global_store_dwordx4 v[154:155], v[150:153], off
	v_lshlrev_b32_e32 v158, 16, v146
	v_and_b32_e32 v159, 0xffff0000, v146
	v_or_b32_e32 v150, s2, v0
	v_ashrrev_i32_e32 v151, 31, v150
	v_lshl_add_u64 v[212:213], v[150:151], 2, s[10:11]
	v_mov_b32_e32 v0, v171
	v_pk_fma_f32 v[152:153], v[46:47], v[134:135], v[0:1] op_sel_hi:[1,1,0]
	s_nop 0
	v_pk_mul_f32 v[152:153], v[152:153], v[158:159]
	v_pk_fma_f32 v[150:151], v[48:49], v[136:137], v[0:1] op_sel_hi:[1,1,0]
	v_cvt_pk_bf16_f32 v146, v152, v153
	v_lshlrev_b32_e32 v152, 16, v147
	v_and_b32_e32 v153, 0xffff0000, v147
	v_pk_mul_f32 v[150:151], v[150:151], v[152:153]
	v_pk_fma_f32 v[156:157], v[42:43], v[130:131], v[0:1] op_sel_hi:[1,1,0]
	v_cvt_pk_bf16_f32 v147, v150, v151
	v_lshlrev_b32_e32 v150, 16, v148
	v_and_b32_e32 v151, 0xffff0000, v148
	v_pk_mul_f32 v[150:151], v[156:157], v[150:151]
	v_pk_fma_f32 v[154:155], v[44:45], v[132:133], v[0:1] op_sel_hi:[1,1,0]
	v_cvt_pk_bf16_f32 v148, v150, v151
	v_lshlrev_b32_e32 v150, 16, v149
	v_and_b32_e32 v151, 0xffff0000, v149
	v_pk_mul_f32 v[150:151], v[154:155], v[150:151]
	v_and_b32_e32 v0, 0x7f, v214
	v_cvt_pk_bf16_f32 v149, v150, v151
	v_lshl_add_u64 v[150:151], v[222:223], 0, v[192:193]
	global_store_dwordx4 v[150:151], v[146:149], off
	v_lshlrev_b32_e32 v154, 16, v142
	v_and_b32_e32 v155, 0xffff0000, v142
	v_or_b32_e32 v146, s2, v0
	v_ashrrev_i32_e32 v147, 31, v146
	v_lshl_add_u64 v[214:215], v[146:147], 2, s[10:11]
	v_mov_b32_e32 v0, v172
	v_pk_fma_f32 v[148:149], v[30:31], v[134:135], v[0:1] op_sel_hi:[1,1,0]
	s_nop 0
	v_pk_mul_f32 v[148:149], v[148:149], v[154:155]
	v_pk_fma_f32 v[146:147], v[32:33], v[136:137], v[0:1] op_sel_hi:[1,1,0]
	v_cvt_pk_bf16_f32 v142, v148, v149
	v_lshlrev_b32_e32 v148, 16, v143
	v_and_b32_e32 v149, 0xffff0000, v143
	v_pk_mul_f32 v[146:147], v[146:147], v[148:149]
	v_pk_fma_f32 v[152:153], v[26:27], v[130:131], v[0:1] op_sel_hi:[1,1,0]
	v_cvt_pk_bf16_f32 v143, v146, v147
	v_lshlrev_b32_e32 v146, 16, v144
	v_and_b32_e32 v147, 0xffff0000, v144
	v_pk_mul_f32 v[146:147], v[152:153], v[146:147]
	v_pk_fma_f32 v[150:151], v[28:29], v[132:133], v[0:1] op_sel_hi:[1,1,0]
	v_cvt_pk_bf16_f32 v144, v146, v147
	v_lshlrev_b32_e32 v146, 16, v145
	v_and_b32_e32 v147, 0xffff0000, v145
	v_pk_mul_f32 v[146:147], v[150:151], v[146:147]
	v_and_b32_e32 v0, 0x7f, v216
	v_cvt_pk_bf16_f32 v145, v146, v147
	v_lshl_add_u64 v[146:147], v[222:223], 0, v[190:191]
	global_store_dwordx4 v[146:147], v[142:145], off
	s_nop 1
	v_or_b32_e32 v142, s2, v0
	v_ashrrev_i32_e32 v143, 31, v142
	v_lshl_add_u64 v[216:217], v[142:143], 2, s[10:11]
	v_mov_b32_e32 v0, v173
	s_mov_b64 s[2:3], 0
	v_pk_fma_f32 v[134:135], v[14:15], v[134:135], v[0:1] op_sel_hi:[1,1,0]
	v_pk_fma_f32 v[142:143], v[12:13], v[132:133], v[0:1] op_sel_hi:[1,1,0]
	v_pk_fma_f32 v[132:133], v[10:11], v[130:131], v[0:1] op_sel_hi:[1,1,0]
	v_lshlrev_b32_e32 v130, 16, v138
	v_and_b32_e32 v131, 0xffff0000, v138
	v_pk_fma_f32 v[136:137], v[16:17], v[136:137], v[0:1] op_sel_hi:[1,1,0]
	v_pk_mul_f32 v[130:131], v[134:135], v[130:131]
	v_lshlrev_b32_e32 v134, 16, v139
	v_and_b32_e32 v135, 0xffff0000, v139
	v_pk_mul_f32 v[134:135], v[136:137], v[134:135]
	v_cvt_pk_bf16_f32 v130, v130, v131
	v_cvt_pk_bf16_f32 v131, v134, v135
	v_lshlrev_b32_e32 v134, 16, v140
	v_and_b32_e32 v135, 0xffff0000, v140
	v_add_u32_e32 v138, 0x80, v218
	v_pk_mul_f32 v[132:133], v[132:133], v[134:135]
	v_lshlrev_b32_e32 v134, 16, v141
	v_and_b32_e32 v135, 0xffff0000, v141
	v_ashrrev_i32_e32 v139, 31, v138
	v_pk_mul_f32 v[134:135], v[142:143], v[134:135]
	v_lshlrev_b64 v[218:219], 1, v[138:139]
	v_cvt_pk_bf16_f32 v132, v132, v133
	v_cvt_pk_bf16_f32 v133, v134, v135
	v_lshl_add_u64 v[134:135], v[222:223], 0, v[188:189]
	v_lshl_add_u64 v[138:139], s[76:77], 0, v[218:219]
	global_store_dwordx4 v[134:135], v[130:133], off
	v_lshl_add_u64 v[140:141], v[138:139], 0, v[204:205]
	global_load_dwordx4 v[130:133], v[220:221], off offset:528
	global_load_dwordx4 v[134:137], v[220:221], off offset:512
	v_lshl_add_u64 v[218:219], s[8:9], 0, v[218:219]
	global_load_dwordx4 v[220:223], v[140:141], off
	v_lshl_add_u64 v[140:141], v[138:139], 0, v[202:203]
	global_load_dwordx4 v[162:165], v[140:141], off
	v_lshl_add_u64 v[140:141], v[138:139], 0, v[200:201]
	global_load_dwordx4 v[158:161], v[140:141], off
	v_lshl_add_u64 v[140:141], v[138:139], 0, v[198:199]
	global_load_dwordx4 v[154:157], v[140:141], off
	v_lshl_add_u64 v[140:141], v[138:139], 0, v[194:195]
	global_load_dwordx4 v[150:153], v[140:141], off
	v_lshl_add_u64 v[140:141], v[138:139], 0, v[192:193]
	global_load_dwordx4 v[146:149], v[140:141], off
	v_lshl_add_u64 v[140:141], v[138:139], 0, v[190:191]
	v_lshl_add_u64 v[138:139], v[138:139], 0, v[188:189]
	global_load_dwordx4 v[142:145], v[140:141], off
	v_lshl_add_u64 v[204:205], v[218:219], 0, v[204:205]
	global_load_dwordx4 v[138:141], v[138:139], off
	global_load_dword v0, v[196:197], off
	v_lshl_add_u64 v[202:203], v[218:219], 0, v[202:203]
	s_waitcnt vmcnt(8)
	v_lshlrev_b32_e32 v248, 16, v220
	v_and_b32_e32 v249, 0xffff0000, v220
	s_waitcnt vmcnt(0)
	v_pk_fma_f32 v[242:243], v[118:119], v[134:135], v[0:1] op_sel_hi:[1,1,0]
	s_nop 0
	v_pk_mul_f32 v[242:243], v[242:243], v[248:249]
	v_pk_fma_f32 v[240:241], v[120:121], v[136:137], v[0:1] op_sel_hi:[1,1,0]
	v_cvt_pk_bf16_f32 v220, v242, v243
	v_lshlrev_b32_e32 v242, 16, v221
	v_and_b32_e32 v243, 0xffff0000, v221
	v_pk_mul_f32 v[240:241], v[240:241], v[242:243]
	v_pk_fma_f32 v[246:247], v[114:115], v[130:131], v[0:1] op_sel_hi:[1,1,0]
	v_cvt_pk_bf16_f32 v221, v240, v241
	v_lshlrev_b32_e32 v240, 16, v222
	v_and_b32_e32 v241, 0xffff0000, v222
	v_pk_mul_f32 v[240:241], v[246:247], v[240:241]
	v_pk_fma_f32 v[244:245], v[116:117], v[132:133], v[0:1] op_sel_hi:[1,1,0]
	v_cvt_pk_bf16_f32 v222, v240, v241
	v_lshlrev_b32_e32 v240, 16, v223
	v_and_b32_e32 v241, 0xffff0000, v223
	v_pk_mul_f32 v[240:241], v[244:245], v[240:241]
	s_nop 0
	v_cvt_pk_bf16_f32 v223, v240, v241
	global_store_dwordx4 v[204:205], v[220:223], off
	v_mov_b32_e32 v0, v171
	v_lshlrev_b32_e32 v240, 16, v162
	v_and_b32_e32 v241, 0xffff0000, v162
	v_pk_fma_f32 v[206:207], v[102:103], v[134:135], v[0:1] op_sel_hi:[1,1,0]
	s_nop 0
	v_pk_mul_f32 v[206:207], v[206:207], v[240:241]
	v_pk_fma_f32 v[204:205], v[104:105], v[136:137], v[0:1] op_sel_hi:[1,1,0]
	v_cvt_pk_bf16_f32 v162, v206, v207
	v_lshlrev_b32_e32 v206, 16, v163
	v_and_b32_e32 v207, 0xffff0000, v163
	v_pk_mul_f32 v[204:205], v[204:205], v[206:207]
	v_pk_fma_f32 v[222:223], v[98:99], v[130:131], v[0:1] op_sel_hi:[1,1,0]
	v_cvt_pk_bf16_f32 v163, v204, v205
	v_lshlrev_b32_e32 v204, 16, v164
	v_and_b32_e32 v205, 0xffff0000, v164
	v_pk_mul_f32 v[204:205], v[222:223], v[204:205]
	v_pk_fma_f32 v[220:221], v[100:101], v[132:133], v[0:1] op_sel_hi:[1,1,0]
	v_cvt_pk_bf16_f32 v164, v204, v205
	v_lshlrev_b32_e32 v204, 16, v165
	v_and_b32_e32 v205, 0xffff0000, v165
	v_pk_mul_f32 v[204:205], v[220:221], v[204:205]
	v_lshlrev_b32_e32 v206, 16, v158
	v_cvt_pk_bf16_f32 v165, v204, v205
	global_store_dwordx4 v[202:203], v[162:165], off
	v_mov_b32_e32 v0, v172
	v_and_b32_e32 v207, 0xffff0000, v158
	v_pk_fma_f32 v[164:165], v[86:87], v[134:135], v[0:1] op_sel_hi:[1,1,0]
	s_nop 0
	v_pk_mul_f32 v[164:165], v[164:165], v[206:207]
	v_pk_fma_f32 v[162:163], v[88:89], v[136:137], v[0:1] op_sel_hi:[1,1,0]
	v_cvt_pk_bf16_f32 v158, v164, v165
	v_lshlrev_b32_e32 v164, 16, v159
	v_and_b32_e32 v165, 0xffff0000, v159
	v_pk_mul_f32 v[162:163], v[162:163], v[164:165]
	v_pk_fma_f32 v[204:205], v[82:83], v[130:131], v[0:1] op_sel_hi:[1,1,0]
	v_cvt_pk_bf16_f32 v159, v162, v163
	v_lshlrev_b32_e32 v162, 16, v160
	v_and_b32_e32 v163, 0xffff0000, v160
	v_pk_mul_f32 v[162:163], v[204:205], v[162:163]
	v_pk_fma_f32 v[202:203], v[84:85], v[132:133], v[0:1] op_sel_hi:[1,1,0]
	v_cvt_pk_bf16_f32 v160, v162, v163
	v_lshlrev_b32_e32 v162, 16, v161
	v_and_b32_e32 v163, 0xffff0000, v161
	v_pk_mul_f32 v[162:163], v[202:203], v[162:163]
	s_nop 0
	v_cvt_pk_bf16_f32 v161, v162, v163
	v_lshl_add_u64 v[162:163], v[218:219], 0, v[200:201]
	global_store_dwordx4 v[162:163], v[158:161], off
	v_mov_b32_e32 v0, v173
	v_lshlrev_b32_e32 v200, 16, v154
	v_and_b32_e32 v201, 0xffff0000, v154
	v_pk_fma_f32 v[160:161], v[70:71], v[134:135], v[0:1] op_sel_hi:[1,1,0]
	s_nop 0
	v_pk_mul_f32 v[160:161], v[160:161], v[200:201]
	v_pk_fma_f32 v[158:159], v[72:73], v[136:137], v[0:1] op_sel_hi:[1,1,0]
	v_cvt_pk_bf16_f32 v154, v160, v161
	v_lshlrev_b32_e32 v160, 16, v155
	v_and_b32_e32 v161, 0xffff0000, v155
	v_pk_mul_f32 v[158:159], v[158:159], v[160:161]
	v_pk_fma_f32 v[164:165], v[66:67], v[130:131], v[0:1] op_sel_hi:[1,1,0]
	v_cvt_pk_bf16_f32 v155, v158, v159
	v_lshlrev_b32_e32 v158, 16, v156
	v_and_b32_e32 v159, 0xffff0000, v156
	v_pk_mul_f32 v[158:159], v[164:165], v[158:159]
	v_pk_fma_f32 v[162:163], v[68:69], v[132:133], v[0:1] op_sel_hi:[1,1,0]
	v_cvt_pk_bf16_f32 v156, v158, v159
	v_lshlrev_b32_e32 v158, 16, v157
	v_and_b32_e32 v159, 0xffff0000, v157
	v_pk_mul_f32 v[158:159], v[162:163], v[158:159]
	v_lshlrev_b32_e32 v162, 16, v150
	v_cvt_pk_bf16_f32 v157, v158, v159
	v_lshl_add_u64 v[158:159], v[218:219], 0, v[198:199]
	global_store_dwordx4 v[158:159], v[154:157], off
	v_mov_b32_e32 v0, v170
	v_and_b32_e32 v163, 0xffff0000, v150
	v_pk_fma_f32 v[156:157], v[54:55], v[134:135], v[0:1] op_sel_hi:[1,1,0]
	s_nop 0
	v_pk_mul_f32 v[156:157], v[156:157], v[162:163]
	v_pk_fma_f32 v[154:155], v[56:57], v[136:137], v[0:1] op_sel_hi:[1,1,0]
	v_cvt_pk_bf16_f32 v150, v156, v157
	v_lshlrev_b32_e32 v156, 16, v151
	v_and_b32_e32 v157, 0xffff0000, v151
	v_pk_mul_f32 v[154:155], v[154:155], v[156:157]
	v_pk_fma_f32 v[160:161], v[50:51], v[130:131], v[0:1] op_sel_hi:[1,1,0]
	v_cvt_pk_bf16_f32 v151, v154, v155
	v_lshlrev_b32_e32 v154, 16, v152
	v_and_b32_e32 v155, 0xffff0000, v152
	v_pk_mul_f32 v[154:155], v[160:161], v[154:155]
	v_pk_fma_f32 v[158:159], v[52:53], v[132:133], v[0:1] op_sel_hi:[1,1,0]
	v_cvt_pk_bf16_f32 v152, v154, v155
	v_lshlrev_b32_e32 v154, 16, v153
	v_and_b32_e32 v155, 0xffff0000, v153
	v_pk_mul_f32 v[154:155], v[158:159], v[154:155]
	v_lshlrev_b32_e32 v158, 16, v146
	v_cvt_pk_bf16_f32 v153, v154, v155
	v_lshl_add_u64 v[154:155], v[218:219], 0, v[194:195]
	global_store_dwordx4 v[154:155], v[150:153], off
	v_mov_b32_e32 v0, v171
	v_and_b32_e32 v159, 0xffff0000, v146
	v_pk_fma_f32 v[152:153], v[38:39], v[134:135], v[0:1] op_sel_hi:[1,1,0]
	s_nop 0
	v_pk_mul_f32 v[152:153], v[152:153], v[158:159]
	v_pk_fma_f32 v[150:151], v[40:41], v[136:137], v[0:1] op_sel_hi:[1,1,0]
	v_cvt_pk_bf16_f32 v146, v152, v153
	v_lshlrev_b32_e32 v152, 16, v147
	v_and_b32_e32 v153, 0xffff0000, v147
	v_pk_mul_f32 v[150:151], v[150:151], v[152:153]
	v_pk_fma_f32 v[156:157], v[34:35], v[130:131], v[0:1] op_sel_hi:[1,1,0]
	v_cvt_pk_bf16_f32 v147, v150, v151
	v_lshlrev_b32_e32 v150, 16, v148
	v_and_b32_e32 v151, 0xffff0000, v148
	v_pk_mul_f32 v[150:151], v[156:157], v[150:151]
	v_pk_fma_f32 v[154:155], v[36:37], v[132:133], v[0:1] op_sel_hi:[1,1,0]
	v_cvt_pk_bf16_f32 v148, v150, v151
	v_lshlrev_b32_e32 v150, 16, v149
	v_and_b32_e32 v151, 0xffff0000, v149
	v_pk_mul_f32 v[150:151], v[154:155], v[150:151]
	v_lshlrev_b32_e32 v154, 16, v142
	v_cvt_pk_bf16_f32 v149, v150, v151
	v_lshl_add_u64 v[150:151], v[218:219], 0, v[192:193]
	global_store_dwordx4 v[150:151], v[146:149], off
	v_mov_b32_e32 v0, v172
	v_and_b32_e32 v155, 0xffff0000, v142
	v_pk_fma_f32 v[148:149], v[22:23], v[134:135], v[0:1] op_sel_hi:[1,1,0]
	s_nop 0
	v_pk_mul_f32 v[148:149], v[148:149], v[154:155]
	v_pk_fma_f32 v[146:147], v[24:25], v[136:137], v[0:1] op_sel_hi:[1,1,0]
	v_cvt_pk_bf16_f32 v142, v148, v149
	v_lshlrev_b32_e32 v148, 16, v143
	v_and_b32_e32 v149, 0xffff0000, v143
	v_pk_mul_f32 v[146:147], v[146:147], v[148:149]
	v_pk_fma_f32 v[152:153], v[18:19], v[130:131], v[0:1] op_sel_hi:[1,1,0]
	v_cvt_pk_bf16_f32 v143, v146, v147
	v_lshlrev_b32_e32 v146, 16, v144
	v_and_b32_e32 v147, 0xffff0000, v144
	v_pk_mul_f32 v[146:147], v[152:153], v[146:147]
	v_pk_fma_f32 v[150:151], v[20:21], v[132:133], v[0:1] op_sel_hi:[1,1,0]
	v_cvt_pk_bf16_f32 v144, v146, v147
	v_lshlrev_b32_e32 v146, 16, v145
	v_and_b32_e32 v147, 0xffff0000, v145
	v_pk_mul_f32 v[146:147], v[150:151], v[146:147]
	s_nop 0
	v_cvt_pk_bf16_f32 v145, v146, v147
	v_lshl_add_u64 v[146:147], v[218:219], 0, v[190:191]
	global_store_dwordx4 v[146:147], v[142:145], off
	v_mov_b32_e32 v0, v173
	v_pk_fma_f32 v[134:135], v[6:7], v[134:135], v[0:1] op_sel_hi:[1,1,0]
	v_pk_fma_f32 v[142:143], v[4:5], v[132:133], v[0:1] op_sel_hi:[1,1,0]
	v_pk_fma_f32 v[132:133], v[2:3], v[130:131], v[0:1] op_sel_hi:[1,1,0]
	v_lshlrev_b32_e32 v130, 16, v138
	v_and_b32_e32 v131, 0xffff0000, v138
	v_pk_fma_f32 v[136:137], v[8:9], v[136:137], v[0:1] op_sel_hi:[1,1,0]
	v_pk_mul_f32 v[130:131], v[134:135], v[130:131]
	v_lshlrev_b32_e32 v134, 16, v139
	v_and_b32_e32 v135, 0xffff0000, v139
	v_pk_mul_f32 v[134:135], v[136:137], v[134:135]
	v_cvt_pk_bf16_f32 v130, v130, v131
	v_cvt_pk_bf16_f32 v131, v134, v135
	v_lshlrev_b32_e32 v134, 16, v140
	v_and_b32_e32 v135, 0xffff0000, v140
	v_pk_mul_f32 v[132:133], v[132:133], v[134:135]
	v_lshlrev_b32_e32 v134, 16, v141
	v_and_b32_e32 v135, 0xffff0000, v141
	v_pk_mul_f32 v[134:135], v[142:143], v[134:135]
	v_cvt_pk_bf16_f32 v132, v132, v133
	v_cvt_pk_bf16_f32 v133, v134, v135
	v_lshl_add_u64 v[134:135], v[218:219], 0, v[188:189]
	global_store_dwordx4 v[134:135], v[130:133], off
